# scan prepper: two alternating input register sets (prefetch lands directly in the set the next chunk's math reads; 23 staging copies per chunk removed), confirmed with scan phases repeated 4x
# speedup vs baseline: 1.0097x; 1.0005x over previous
.LBB0_329:
	s_or_b64 exec, exec, s[16:17]
	v_cndmask_b32_e64 v36, v137, v136, s[40:41]
	s_lshl_b32 s28, s72, 6
	v_add_u32_e32 v38, s26, v36
	v_mov_b64_e32 v[36:37], s[2:3]
	v_mad_i64_i32 v[86:87], s[16:17], v38, s63, v[36:37]
	s_lshl_b32 s28, s28, 1
	s_mov_b32 s29, s7
	v_lshl_add_u64 v[36:37], v[86:87], 0, s[28:29]
	v_lshl_add_u64 v[36:37], v[74:75], 1, v[36:37]
	v_add_co_u32_e32 v48, vcc, 0x1000, v36
	v_lshl_add_u64 v[88:89], v[86:87], 0, s[6:7]
	s_nop 0
	v_addc_co_u32_e32 v49, vcc, 0, v37, vcc
	v_add_co_u32_e32 v88, vcc, 0x1000, v88
	v_lshl_add_u64 v[86:87], v[84:85], 1, v[86:87]
	s_nop 0
	v_addc_co_u32_e32 v89, vcc, 0, v89, vcc
	v_add_co_u32_e32 v92, vcc, 0x1000, v86
	v_lshl_add_u64 v[38:39], v[36:37], 0, s[66:67]
	v_lshl_add_u64 v[36:37], v[36:37], 0, s[36:37]
	v_addc_co_u32_e32 v93, vcc, 0, v87, vcc
	s_waitcnt lgkmcnt(6)
	global_load_dwordx4 v[216:219], v[48:49], off offset:2304
	global_load_dwordx4 v[204:207], v[36:37], off offset:64
	s_nop 0
	global_load_dwordx4 v[220:223], v[38:39], off offset:64
	s_nop 0
	global_load_dwordx4 v[200:203], v[48:49], off offset:2048
	s_nop 0
	global_load_dword v212, v[88:89], off offset:2816
	s_nop 0
	global_load_dwordx2 v[226:227], v[92:93], off
	s_nop 0
	global_load_dwordx2 v[214:215], v[86:87], off offset:2048
	global_load_dwordx2 v[224:225], v[86:87], off
	s_lshl_b32 s16, s70, 3
	s_add_u32 s16, s44, s16
	s_addc_u32 s17, s45, 0
	s_lshl_b32 s29, s72, 2
	s_add_u32 s42, s16, s29
	s_waitcnt lgkmcnt(0)
	s_barrier
	s_addc_u32 s43, s17, 0
	s_lshl_b32 s16, s27, 2
	s_mov_b32 s17, s7
	s_ashr_i32 s27, s26, 31
	v_lshl_add_u64 v[86:87], v[76:77], 0, s[16:17]
	s_lshl_b64 s[16:17], s[26:27], 12
	s_mov_b32 s73, 0
	v_lshl_add_u64 v[86:87], v[86:87], 0, s[16:17]
	s_mov_b32 s27, s46
	s_mov_b32 s29, 0
	s_mov_b32 s74, 0
.Lpp_chunk:
	s_add_i32 s75, s74, 1
	s_cmp_ge_u32 s75, s31
	s_cbranch_scc1 .Lpp_cs
	s_waitcnt vmcnt(0)
.Lpp_cs:
	s_and_saveexec_b64 s[16:17], s[4:5]
	s_cbranch_execz .Lpp_cs_done
	v_lshl_add_u32 v110, s33, 9, v134
	ds_read_b128 v[112:115], v110 offset:49920
	v_add_u32_e32 v110, s73, v69
	v_add_u32_e32 v116, s27, v146
	v_cndmask_b32_e64 v110, v116, v110, s[40:41]
	s_waitcnt lgkmcnt(0)
	v_mov_b32_e32 v116, v113
	v_mov_b32_e32 v117, v114
	v_mov_b32_e32 v113, v115
	v_pk_add_f32 v[112:113], v[116:117], v[112:113]
	s_nop 0
	v_add_f32_e32 v114, v112, v113
	v_add_u32_e32 v112, s26, v110
	v_ashrrev_i32_e32 v113, 31, v112
	v_lshlrev_b64 v[112:113], 7, v[112:113]
	v_lshl_add_u64 v[112:113], s[42:43], 0, v[112:113]
	global_store_dword v[112:113], v114, off
.Lpp_cs_done:
	s_or_b64 exec, exec, s[16:17]
	s_xor_b32 s33, s33, 1
	s_cmp_ge_u32 s75, s31
	s_cbranch_scc1 .Lpp_nomore
	s_add_i32 s16, s74, 2
	s_cmp_ge_u32 s16, s31
	s_cbranch_scc1 .Lpp_nopf
	v_lshl_or_b32 v110, s16, 4, v68
	v_xad_u32 v111, v110, -1, s46
	v_cndmask_b32_e64 v110, v111, v110, s[40:41]
	v_add_u32_e32 v112, s26, v110
	v_mov_b64_e32 v[110:111], s[2:3]
	v_mad_i64_i32 v[110:111], s[16:17], v112, s63, v[110:111]
	v_lshl_add_u64 v[114:115], v[84:85], 1, v[110:111]
	v_lshl_add_u64 v[116:117], v[110:111], 0, s[6:7]
	v_lshl_add_u64 v[110:111], v[110:111], 0, s[28:29]
	v_lshl_add_u64 v[118:119], v[74:75], 1, v[110:111]
	v_lshl_add_u64 v[120:121], v[118:119], 0, s[36:37]
	v_lshl_add_u64 v[122:123], v[118:119], 0, s[66:67]
	v_lshl_add_u64 v[124:125], v[114:115], 0, s[92:93]
	v_lshl_add_u64 v[126:127], v[116:117], 0, s[92:93]
	v_lshl_add_u64 v[128:129], v[118:119], 0, s[92:93]
	global_load_dwordx2 v[94:95], v[114:115], off
	global_load_dwordx2 v[50:51], v[114:115], off offset:2048
	global_load_dwordx2 v[96:97], v[124:125], off
	global_load_dword v48, v[126:127], off offset:2816
	global_load_dwordx4 v[36:39], v[128:129], off offset:2048
	global_load_dwordx4 v[86:89], v[128:129], off offset:2304
	global_load_dwordx4 v[40:43], v[120:121], off offset:64
	global_load_dwordx4 v[90:93], v[122:123], off offset:64
.Lpp_nopf:
	s_mul_i32 s16, s33, 0x6100
	v_mfma_f32_16x16x32_bf16 v[200:203], v[0:3], v[200:203], 0
	v_mfma_f32_16x16x32_bf16 v[208:211], v[4:7], v[204:207], v[200:203]
	v_mfma_f32_16x16x32_bf16 v[200:203], v[8:11], v[216:219], 0
	v_lshlrev_b32_e32 v218, 16, v214
	s_nop 5
	v_add_f32_e32 v208, v16, v208
	v_add_f32_e32 v209, v17, v209
	v_mfma_f32_16x16x32_bf16 v[204:207], v[12:15], v[220:223], v[200:203]
	v_mul_f32_e32 v208, 0xbfb8aa3b, v208
	v_mul_f32_e32 v209, 0xbfb8aa3b, v209
	v_exp_f32_e32 v208, v208
	v_exp_f32_e32 v209, v209
	v_add_f32_e32 v210, v18, v210
	s_nop 2
	v_add_f32_e32 v206, v22, v206
	v_mul_f32_e32 v206, 0xbfb8aa3b, v206
	v_exp_f32_e32 v206, v206
	v_add_f32_e32 v208, 1.0, v208
	v_add_f32_e32 v209, 1.0, v209
	v_rcp_f32_e32 v208, v208
	v_add_f32_e32 v206, 1.0, v206
	v_rcp_f32_e32 v222, v206
	v_add_f32_e32 v206, v19, v211
	v_mul_f32_e32 v206, 0xbfb8aa3b, v206
	v_exp_f32_e32 v206, v206
	v_rcp_f32_e32 v209, v209
	v_add_f32_e32 v204, v20, v204
	v_add_f32_e32 v205, v21, v205
	v_add_f32_e32 v206, 1.0, v206
	v_rcp_f32_e32 v206, v206
	v_mul_f32_e32 v210, 0xbfb8aa3b, v210
	v_mul_f32_e32 v204, 0xbfb8aa3b, v204
	v_mul_f32_e32 v205, 0xbfb8aa3b, v205
	v_mul_f32_e32 v206, 0xbf1b4598, v206
	v_mul_f32_e32 v206, 0x3fb8aa3b, v206
	v_exp_f32_e32 v211, v206
	v_add_f32_e32 v206, v23, v207
	v_exp_f32_e32 v210, v210
	v_mul_f32_e32 v206, 0xbfb8aa3b, v206
	v_mul_f32_e32 v208, 0xbf1b4598, v208
	v_exp_f32_e32 v204, v204
	v_mul_f32_e32 v209, 0xbf1b4598, v209
	v_exp_f32_e32 v205, v205
	v_exp_f32_e32 v206, v206
	v_mul_f32_e32 v208, 0x3fb8aa3b, v208
	v_mul_f32_e32 v209, 0x3fb8aa3b, v209
	v_exp_f32_e32 v208, v208
	v_exp_f32_e32 v209, v209
	v_add_f32_e32 v210, 1.0, v210
	v_add_f32_e32 v204, 1.0, v204
	v_add_f32_e32 v205, 1.0, v205
	v_rcp_f32_e32 v210, v210
	v_add_f32_e32 v206, 1.0, v206
	v_rcp_f32_e32 v204, v204
	v_rcp_f32_e32 v205, v205
	v_rcp_f32_e32 v223, v206
	v_mov_b32_e32 v206, 1.0
	v_mov_b32_e32 v207, 1.0
	v_mul_f32_e32 v210, 0xbf1b4598, v210
	v_mov_b32_dpp v206, v208 row_shr:1 row_mask:0xf bank_mask:0xf
	v_mov_b32_dpp v207, v209 row_shr:1 row_mask:0xf bank_mask:0xf
	v_pk_mul_f32 v[206:207], v[208:209], v[206:207]
	v_mov_b32_e32 v208, 1.0
	v_mov_b32_e32 v209, 1.0
	v_mul_f32_e32 v210, 0x3fb8aa3b, v210
	v_mov_b32_dpp v208, v206 row_shr:2 row_mask:0xf bank_mask:0xf
	v_mov_b32_dpp v209, v207 row_shr:2 row_mask:0xf bank_mask:0xf
	v_pk_mul_f32 v[206:207], v[206:207], v[208:209]
	v_mov_b32_e32 v208, 1.0
	v_mov_b32_e32 v209, 1.0
	v_pk_add_f32 v[104:105], v[222:223], -1.0 op_sel_hi:[1,0]
	v_pk_add_f32 v[106:107], v[204:205], -1.0 op_sel_hi:[1,0]
	v_and_b32_e32 v219, 0xffff0000, v214
	v_lshlrev_b32_e32 v220, 16, v215
	v_and_b32_e32 v221, 0xffff0000, v215
	v_exp_f32_e32 v210, v210
	v_mov_b32_dpp v208, v206 row_shr:4 row_mask:0xf bank_mask:0xf
	v_mov_b32_dpp v209, v207 row_shr:4 row_mask:0xf bank_mask:0xf
	v_pk_fma_f32 v[106:107], v[28:29], v[106:107], 1.0 op_sel_hi:[1,1,0]
	v_pk_fma_f32 v[104:105], v[30:31], v[104:105], 1.0 op_sel_hi:[1,1,0]
	v_lshlrev_b32_e32 v214, 16, v224
	v_and_b32_e32 v215, 0xffff0000, v224
	v_lshlrev_b32_e32 v216, 16, v225
	v_and_b32_e32 v217, 0xffff0000, v225
	v_pk_mul_f32 v[206:207], v[206:207], v[208:209]
	v_mov_b32_e32 v208, 1.0
	v_mov_b32_e32 v209, 1.0
	v_pk_mul_f32 v[102:103], v[24:25], v[218:219]
	v_pk_mul_f32 v[104:105], v[104:105], v[220:221]
	v_pk_mul_f32 v[106:107], v[106:107], v[218:219]
	v_mov_b32_dpp v208, v206 row_shr:8 row_mask:0xf bank_mask:0xf
	v_mov_b32_dpp v209, v207 row_shr:8 row_mask:0xf bank_mask:0xf
	v_pk_mul_f32 v[108:109], v[102:103], v[204:205]
	v_pk_mul_f32 v[204:205], v[106:107], v[214:215]
	v_pk_mul_f32 v[218:219], v[104:105], v[216:217]
	v_pk_mul_f32 v[206:207], v[206:207], v[208:209]
	v_mov_b32_e32 v208, 1.0
	v_mov_b32_e32 v209, 1.0
	v_pk_mul_f32 v[218:219], v[34:35], v[218:219]
	v_pk_mul_f32 v[204:205], v[32:33], v[204:205]
	v_mov_b32_dpp v208, v210 row_shr:1 row_mask:0xf bank_mask:0xf
	v_mov_b32_dpp v209, v211 row_shr:1 row_mask:0xf bank_mask:0xf
	v_add_f32_e32 v204, v204, v205
	v_add_f32_e32 v205, v218, v219
	v_pk_mul_f32 v[208:209], v[210:211], v[208:209]
	v_mov_b32_e32 v210, 1.0
	v_mov_b32_e32 v211, 1.0
	v_add_f32_e32 v204, v204, v205
	v_mov_b32_dpp v210, v208 row_shr:2 row_mask:0xf bank_mask:0xf
	v_mov_b32_dpp v211, v209 row_shr:2 row_mask:0xf bank_mask:0xf
	ds_bpermute_b32 v205, v142, v204
	v_pk_mul_f32 v[208:209], v[208:209], v[210:211]
	v_mov_b32_e32 v210, 1.0
	v_mov_b32_e32 v211, 1.0
	v_lshlrev_b32_e32 v200, 16, v226
	v_mov_b32_dpp v210, v208 row_shr:4 row_mask:0xf bank_mask:0xf
	v_mov_b32_dpp v211, v209 row_shr:4 row_mask:0xf bank_mask:0xf
	v_pk_mul_f32 v[208:209], v[208:209], v[210:211]
	v_mov_b32_e32 v210, 1.0
	v_mov_b32_e32 v211, 1.0
	s_waitcnt lgkmcnt(0)
	v_add_f32_e32 v204, v204, v205
	v_mov_b32_dpp v210, v208 row_shr:8 row_mask:0xf bank_mask:0xf
	v_mov_b32_dpp v211, v209 row_shr:8 row_mask:0xf bank_mask:0xf
	v_pk_mul_f32 v[208:209], v[208:209], v[210:211]
	v_and_b32_e32 v201, 0xffff0000, v226
	v_lshlrev_b32_e32 v202, 16, v227
	v_and_b32_e32 v203, 0xffff0000, v227
	v_rcp_f32_e32 v226, v206
	v_rcp_f32_e32 v227, v207
	v_rcp_f32_e32 v228, v208
	v_rcp_f32_e32 v229, v209
	ds_bpermute_b32 v205, v143, v204
	v_mov_b32_e32 v224, 1.0
	v_mov_b32_e32 v225, 1.0
	v_mov_b32_e32 v210, 1.0
	v_mov_b32_e32 v211, 1.0
	v_mov_b32_dpp v224, v206 row_shr:1 row_mask:0xf bank_mask:0xf
	v_mov_b32_dpp v225, v207 row_shr:1 row_mask:0xf bank_mask:0xf
	v_mov_b32_dpp v210, v208 row_shr:1 row_mask:0xf bank_mask:0xf
	v_mov_b32_dpp v211, v209 row_shr:1 row_mask:0xf bank_mask:0xf
	v_pk_mul_f32 v[100:101], v[26:27], v[220:221]
	v_pk_mul_f32 v[218:219], v[102:103], v[224:225]
	v_pk_mul_f32 v[222:223], v[100:101], v[222:223]
	v_pk_mul_f32 v[210:211], v[100:101], v[210:211]
	v_pk_mul_f32 v[218:219], v[212:213], v[218:219] op_sel_hi:[0,1] neg_lo:[1,0] neg_hi:[1,0]
	v_pk_mul_f32 v[220:221], v[212:213], v[210:211] op_sel_hi:[0,1] neg_lo:[1,0] neg_hi:[1,0]
	v_pk_mul_f32 v[212:213], v[222:223], v[228:229]
	v_pk_mul_f32 v[210:211], v[108:109], v[226:227]
	v_pk_mul_f32 v[222:223], v[106:107], v[226:227]
	v_pk_mul_f32 v[226:227], v[206:207], v[214:215]
	v_add_u32_e32 v214, s16, v133
	v_pk_mul_f32 v[224:225], v[104:105], v[228:229]
	v_pk_mul_f32 v[228:229], v[208:209], v[216:217]
	ds_write_b128 v214, v[206:209]
	ds_write_b128 v214, v[218:221] offset:256
	ds_write_b128 v214, v[210:213] offset:512
	ds_write_b128 v214, v[222:225] offset:768
	ds_write_b128 v214, v[226:229] offset:1024
	ds_write_b128 v214, v[200:203] offset:1280
	s_and_saveexec_b64 s[16:17], s[38:39]
	s_cbranch_execz .Lpp_math_end
	v_lshl_add_u32 v200, s33, 9, v135
	s_waitcnt lgkmcnt(6)
	v_add_f32_e32 v201, v204, v205
	ds_write_b32 v200, v201 offset:49920

.Lpp_nomore:
	s_waitcnt lgkmcnt(0)
	s_barrier
	s_add_i32 s73, s73, 16
	s_add_i32 s27, s27, -16
	s_mov_b32 s74, s75
	s_cmp_lt_u32 s74, s31
	s_cbranch_scc1 .Lpp_chunkY
	s_branch .Lpp_loop_done
.Lpp_chunkY:
	s_add_i32 s75, s74, 1
	s_cmp_ge_u32 s75, s31
	s_cbranch_scc1 .Lpp_csY
	s_waitcnt vmcnt(0)
.Lpp_csY:
	s_and_saveexec_b64 s[16:17], s[4:5]
	s_cbranch_execz .Lpp_cs_doneY
	v_lshl_add_u32 v110, s33, 9, v134
	ds_read_b128 v[112:115], v110 offset:49920
	v_add_u32_e32 v110, s73, v69
	v_add_u32_e32 v116, s27, v146
	v_cndmask_b32_e64 v110, v116, v110, s[40:41]
	s_waitcnt lgkmcnt(0)
	v_mov_b32_e32 v116, v113
	v_mov_b32_e32 v117, v114
	v_mov_b32_e32 v113, v115
	v_pk_add_f32 v[112:113], v[116:117], v[112:113]
	s_nop 0
	v_add_f32_e32 v114, v112, v113
	v_add_u32_e32 v112, s26, v110
	v_ashrrev_i32_e32 v113, 31, v112
	v_lshlrev_b64 v[112:113], 7, v[112:113]
	v_lshl_add_u64 v[112:113], s[42:43], 0, v[112:113]
	global_store_dword v[112:113], v114, off
.Lpp_cs_doneY:
	s_or_b64 exec, exec, s[16:17]
	s_xor_b32 s33, s33, 1
	s_cmp_ge_u32 s75, s31
	s_cbranch_scc1 .Lpp_nomoreY
	s_add_i32 s16, s74, 2
	s_cmp_ge_u32 s16, s31
	s_cbranch_scc1 .Lpp_nopfY
	v_lshl_or_b32 v110, s16, 4, v68
	v_xad_u32 v111, v110, -1, s46
	v_cndmask_b32_e64 v110, v111, v110, s[40:41]
	v_add_u32_e32 v112, s26, v110
	v_mov_b64_e32 v[110:111], s[2:3]
	v_mad_i64_i32 v[110:111], s[16:17], v112, s63, v[110:111]
	v_lshl_add_u64 v[114:115], v[84:85], 1, v[110:111]
	v_lshl_add_u64 v[116:117], v[110:111], 0, s[6:7]
	v_lshl_add_u64 v[110:111], v[110:111], 0, s[28:29]
	v_lshl_add_u64 v[118:119], v[74:75], 1, v[110:111]
	v_lshl_add_u64 v[120:121], v[118:119], 0, s[36:37]
	v_lshl_add_u64 v[122:123], v[118:119], 0, s[66:67]
	v_lshl_add_u64 v[124:125], v[114:115], 0, s[92:93]
	v_lshl_add_u64 v[126:127], v[116:117], 0, s[92:93]
	v_lshl_add_u64 v[128:129], v[118:119], 0, s[92:93]
	global_load_dwordx2 v[224:225], v[114:115], off
	global_load_dwordx2 v[214:215], v[114:115], off offset:2048
	global_load_dwordx2 v[226:227], v[124:125], off
	global_load_dword v212, v[126:127], off offset:2816
	global_load_dwordx4 v[200:203], v[128:129], off offset:2048
	global_load_dwordx4 v[216:219], v[128:129], off offset:2304
	global_load_dwordx4 v[204:207], v[120:121], off offset:64
	global_load_dwordx4 v[220:223], v[122:123], off offset:64

.Lpp_loop_done:
.LBB0_337:
	s_and_b64 vcc, exec, s[10:11]
	s_cbranch_vccz .LBB0_323
	s_lshl_b32 s6, s71, 2
	s_add_i32 s6, s6, s47
	s_or_b32 s6, s6, s72
	s_lshl_b32 s6, s6, 4
	s_or_b32 s16, s6, s70
	s_ashr_i32 s17, s16, 31
	s_lshl_b64 s[16:17], s[16:17], 14
	v_lshl_add_u64 v[0:1], v[82:83], 0, s[16:17]
	global_store_dwordx4 v[0:1], v[64:67], off
	global_store_dwordx4 v[0:1], v[60:63], off offset:256
	global_store_dwordx4 v[0:1], v[56:59], off offset:16
	global_store_dwordx4 v[0:1], v[52:55], off offset:272
	s_branch .LBB0_323
